# v045 + prologue gain-scaled weight transposes: 8 weight + 8 gain loads issued together per iteration (was load-wait-multiply per element)
# speedup vs baseline: 1.0023x; 1.0023x over previous
; #define LAS __attribute__((address_space(3)))
; __device__ __forceinline__ void transpose_item(const gfloat* W, int K, int N, gbf16* WT, int mode, LAS float* scr, int item, int lane, const gfloat* gain = nullptr) {
;     const int nblk = N / 32, kb = item / nblk, nb = item % nblk, k0 = 64 * kb, n0 = 32 * nb;
; #pragma unroll 8
;     for (int i = 0; i < 32; ++i) { const int kk = 2 * i + (lane >> 5); float w = W[(size_t)(k0 + kk) * N + n0 + (lane & 31)]; if (gain) w *= gain[k0 + kk]; scr[kk * 33 + (lane & 31)] = w; }
;     asm volatile("s_waitcnt lgkmcnt(0)" ::: "memory");
.LBB0_61:
	s_and_b64 vcc, exec, s[22:23]
	s_cbranch_vccz .Lgain_orig_a
	v_lshl_add_u64 v[56:57], v[54:55], 0, s[16:17]
	global_load_dword v100, v[56:57], off
	v_lshl_add_u64 v[56:57], v[52:53], 0, s[16:17]
	global_load_dword v101, v[56:57], off
	v_lshl_add_u64 v[56:57], v[50:51], 0, s[16:17]
	global_load_dword v102, v[56:57], off
	v_lshl_add_u64 v[56:57], v[48:49], 0, s[16:17]
	global_load_dword v103, v[56:57], off
	v_lshl_add_u64 v[56:57], v[46:47], 0, s[16:17]
	global_load_dword v104, v[56:57], off
	v_lshl_add_u64 v[56:57], v[44:45], 0, s[16:17]
	global_load_dword v105, v[56:57], off
	v_lshl_add_u64 v[56:57], v[42:43], 0, s[16:17]
	global_load_dword v106, v[56:57], off
	v_lshl_add_u64 v[56:57], v[38:39], 0, s[16:17]
	global_load_dword v107, v[56:57], off
	v_lshl_add_u64 v[56:57], s[0:1], 0, v[8:9]
	global_load_dword v108, v[56:57], off
	v_lshl_add_u64 v[56:57], s[0:1], 0, v[40:41]
	global_load_dword v109, v[56:57], off offset:8
	global_load_dword v110, v[56:57], off offset:16
	global_load_dword v111, v[56:57], off offset:24
	global_load_dword v112, v[56:57], off offset:32
	global_load_dword v113, v[56:57], off offset:40
	global_load_dword v114, v[56:57], off offset:48
	global_load_dword v115, v[56:57], off offset:56
	s_waitcnt vmcnt(0)
	v_mul_f32_e32 v100, v100, v108
	v_mul_f32_e32 v101, v101, v109
	v_mul_f32_e32 v102, v102, v110
	v_mul_f32_e32 v103, v103, v111
	v_mul_f32_e32 v104, v104, v112
	v_mul_f32_e32 v105, v105, v113
	v_mul_f32_e32 v106, v106, v114
	v_mul_f32_e32 v107, v107, v115
	ds_write_b32 v5, v100
	ds_write_b32 v5, v101 offset:264
	ds_write_b32 v5, v102 offset:528
	ds_write_b32 v5, v103 offset:792
	ds_write_b32 v5, v104 offset:1056
	ds_write_b32 v5, v105 offset:1320
	ds_write_b32 v5, v106 offset:1584
	ds_write_b32 v5, v107 offset:1848
	s_add_u32 s16, s16, 0x50000
	s_addc_u32 s17, s17, 0
	s_add_u32 s0, s0, 64
	s_addc_u32 s1, s1, 0
	v_add_u32_e32 v5, 0x840, v5
	s_cmp_lg_u32 s16, 0x140000
	s_cbranch_scc1 .LBB0_61
	s_branch .LBB0_77

; #define LAS __attribute__((address_space(3)))
; __device__ __forceinline__ void transpose_item(const gfloat* W, int K, int N, gbf16* WT, int mode, LAS float* scr, int item, int lane, const gfloat* gain = nullptr) {
;     const int nblk = N / 32, kb = item / nblk, nb = item % nblk, k0 = 64 * kb, n0 = 32 * nb;
; #pragma unroll 8
;     for (int i = 0; i < 32; ++i) { const int kk = 2 * i + (lane >> 5); float w = W[(size_t)(k0 + kk) * N + n0 + (lane & 31)]; if (gain) w *= gain[k0 + kk]; scr[kk * 33 + (lane & 31)] = w; }
;     asm volatile("s_waitcnt lgkmcnt(0)" ::: "memory");
.LBB0_92:
	s_and_b64 vcc, exec, s[22:23]
	s_cbranch_vccz .Lgain_orig_b
	v_lshl_add_u64 v[56:57], v[54:55], 0, s[16:17]
	global_load_dword v100, v[56:57], off
	v_lshl_add_u64 v[56:57], v[52:53], 0, s[16:17]
	global_load_dword v101, v[56:57], off
	v_lshl_add_u64 v[56:57], v[50:51], 0, s[16:17]
	global_load_dword v102, v[56:57], off
	v_lshl_add_u64 v[56:57], v[48:49], 0, s[16:17]
	global_load_dword v103, v[56:57], off
	v_lshl_add_u64 v[56:57], v[46:47], 0, s[16:17]
	global_load_dword v104, v[56:57], off
	v_lshl_add_u64 v[56:57], v[44:45], 0, s[16:17]
	global_load_dword v105, v[56:57], off
	v_lshl_add_u64 v[56:57], v[42:43], 0, s[16:17]
	global_load_dword v106, v[56:57], off
	v_lshl_add_u64 v[56:57], v[38:39], 0, s[16:17]
	global_load_dword v107, v[56:57], off
	v_lshl_add_u64 v[56:57], s[0:1], 0, v[8:9]
	global_load_dword v108, v[56:57], off
	v_lshl_add_u64 v[56:57], s[0:1], 0, v[40:41]
	global_load_dword v109, v[56:57], off offset:8
	global_load_dword v110, v[56:57], off offset:16
	global_load_dword v111, v[56:57], off offset:24
	global_load_dword v112, v[56:57], off offset:32
	global_load_dword v113, v[56:57], off offset:40
	global_load_dword v114, v[56:57], off offset:48
	global_load_dword v115, v[56:57], off offset:56
	s_waitcnt vmcnt(0)
	v_mul_f32_e32 v100, v100, v108
	v_mul_f32_e32 v101, v101, v109
	v_mul_f32_e32 v102, v102, v110
	v_mul_f32_e32 v103, v103, v111
	v_mul_f32_e32 v104, v104, v112
	v_mul_f32_e32 v105, v105, v113
	v_mul_f32_e32 v106, v106, v114
	v_mul_f32_e32 v107, v107, v115
	ds_write_b32 v5, v100
	ds_write_b32 v5, v101 offset:264
	ds_write_b32 v5, v102 offset:528
	ds_write_b32 v5, v103 offset:792
	ds_write_b32 v5, v104 offset:1056
	ds_write_b32 v5, v105 offset:1320
	ds_write_b32 v5, v106 offset:1584
	ds_write_b32 v5, v107 offset:1848
	s_add_u32 s16, s16, 0x58000
	s_addc_u32 s17, s17, 0
	s_add_u32 s0, s0, 64
	s_addc_u32 s1, s1, 0
	v_add_u32_e32 v5, 0x840, v5
	s_cmp_lg_u32 s16, 0x160000
	s_cbranch_scc1 .LBB0_92
	s_branch .LBB0_108
